# read-once streams (up-projection rows in ffn_act, residual rows in the fused final epilogue) loaded non-temporally
# baseline (speedup 1.0000x reference)
.LBB0_1435:
	s_waitcnt vmcnt(0) lgkmcnt(0)
	s_mov_b64 s[38:39], exec
	v_mov_b32_e32 v204, 0x40135761
	v_mov_b32_e32 v205, 0x40135761
	v_mov_b32_e32 v206, 0x3dd2d3e8
	v_mov_b32_e32 v207, 0x3dd2d3e8
	v_and_b32_e32 v200, 0xff, v172
	v_mad_u32_u24 v197, v172, s15, v199
	v_cmp_ne_u32_e64 s[86:87], 0, v200
	v_cmp_ne_u32_e64 s[88:89], s16, v200
	global_load_dwordx4 v[96:99], v197, s[60:61]
	global_load_dwordx4 v[152:155], v197, s[96:97] nt
	v_subrev_u32_e32 v201, 0x1600, v197
	v_add_u32_e32 v202, 0x1600, v197
	v_cndmask_b32_e64 v201, v197, v201, s[86:87]
	v_cndmask_b32_e64 v202, v197, v202, s[88:89]
	global_load_dwordx4 v[92:95], v201, s[60:61]
	global_load_dwordx4 v[100:103], v202, s[60:61]
	v_add_u32_e32 v172, s12, v172
	v_and_b32_e32 v200, 0xff, v172
	v_mad_u32_u24 v198, v172, s15, v199
	v_cmp_ne_u32_e64 s[50:51], 0, v200
	v_cmp_ne_u32_e64 s[52:53], s16, v200
	global_load_dwordx4 v[132:135], v198, s[60:61]
	global_load_dwordx4 v[156:159], v198, s[96:97] nt
	v_subrev_u32_e32 v201, 0x1600, v198
	v_add_u32_e32 v202, 0x1600, v198
	v_cndmask_b32_e64 v201, v198, v201, s[50:51]
	v_cndmask_b32_e64 v202, v198, v202, s[52:53]
	global_load_dwordx4 v[128:131], v201, s[60:61]
	global_load_dwordx4 v[136:139], v202, s[60:61]
	v_add_u32_e32 v172, s12, v172
	s_waitcnt vmcnt(4)
	v_lshlrev_b32_e32 v216, 16, v96
	v_and_b32_e32 v217, 0xffff0000, v96
	v_lshlrev_b32_e32 v218, 16, v97
	v_and_b32_e32 v219, 0xffff0000, v97
	v_lshlrev_b32_e32 v220, 16, v98
	v_and_b32_e32 v221, 0xffff0000, v98
	v_lshlrev_b32_e32 v222, 16, v99
	v_and_b32_e32 v223, 0xffff0000, v99
	v_fma_f32 v208, v32, v216, v72
	v_fma_f32 v209, v33, v217, v73
	v_fma_f32 v210, v34, v218, v74
	v_fma_f32 v211, v35, v219, v75
	v_fma_f32 v212, v36, v220, v76
	v_fma_f32 v213, v37, v221, v77
	v_fma_f32 v214, v38, v222, v78
	v_fma_f32 v215, v39, v223, v79
	s_mov_b64 exec, s[86:87]
	s_cbranch_execz .Lact_t1_k3
	v_lshlrev_b32_e32 v216, 16, v92
	v_and_b32_e32 v217, 0xffff0000, v92
	v_lshlrev_b32_e32 v218, 16, v93
	v_and_b32_e32 v219, 0xffff0000, v93
	v_lshlrev_b32_e32 v220, 16, v94
	v_and_b32_e32 v221, 0xffff0000, v94
	v_lshlrev_b32_e32 v222, 16, v95
	v_and_b32_e32 v223, 0xffff0000, v95
	v_fmac_f32_e32 v208, v24, v216
	v_fmac_f32_e32 v209, v25, v217
	v_fmac_f32_e32 v210, v26, v218
	v_fmac_f32_e32 v211, v27, v219
	v_fmac_f32_e32 v212, v28, v220
	v_fmac_f32_e32 v213, v29, v221
	v_fmac_f32_e32 v214, v30, v222
	v_fmac_f32_e32 v215, v31, v223

.Lact_ctx_loop:
	v_and_b32_e32 v200, 0xff, v172
	v_mad_u32_u24 v197, v172, s15, v199
	v_cmp_ne_u32_e64 s[86:87], 0, v200
	v_cmp_ne_u32_e64 s[88:89], s16, v200
	global_load_dwordx4 v[96:99], v197, s[60:61]
	global_load_dwordx4 v[152:155], v197, s[96:97] nt
	v_subrev_u32_e32 v201, 0x1600, v197
	v_add_u32_e32 v202, 0x1600, v197
	v_cndmask_b32_e64 v201, v197, v201, s[86:87]
	v_cndmask_b32_e64 v202, v197, v202, s[88:89]
	global_load_dwordx4 v[92:95], v201, s[60:61]
	global_load_dwordx4 v[100:103], v202, s[60:61]
	v_add_u32_e32 v172, s12, v172
	s_waitcnt vmcnt(5)
	v_lshlrev_b32_e32 v216, 16, v132
	v_and_b32_e32 v217, 0xffff0000, v132
	v_lshlrev_b32_e32 v218, 16, v133
	v_and_b32_e32 v219, 0xffff0000, v133
	v_lshlrev_b32_e32 v220, 16, v134
	v_and_b32_e32 v221, 0xffff0000, v134
	v_lshlrev_b32_e32 v222, 16, v135
	v_and_b32_e32 v223, 0xffff0000, v135
	v_fma_f32 v208, v32, v216, v72
	v_fma_f32 v209, v33, v217, v73
	v_fma_f32 v210, v34, v218, v74
	v_fma_f32 v211, v35, v219, v75
	v_fma_f32 v212, v36, v220, v76
	v_fma_f32 v213, v37, v221, v77
	v_fma_f32 v214, v38, v222, v78
	v_fma_f32 v215, v39, v223, v79
	s_mov_b64 exec, s[50:51]
	s_cbranch_execz .Lact_t2_k3
	v_lshlrev_b32_e32 v216, 16, v128
	v_and_b32_e32 v217, 0xffff0000, v128
	v_lshlrev_b32_e32 v218, 16, v129
	v_and_b32_e32 v219, 0xffff0000, v129
	v_lshlrev_b32_e32 v220, 16, v130
	v_and_b32_e32 v221, 0xffff0000, v130
	v_lshlrev_b32_e32 v222, 16, v131
	v_and_b32_e32 v223, 0xffff0000, v131
	v_fmac_f32_e32 v208, v24, v216
	v_fmac_f32_e32 v209, v25, v217
	v_fmac_f32_e32 v210, v26, v218
	v_fmac_f32_e32 v211, v27, v219
	v_fmac_f32_e32 v212, v28, v220
	v_fmac_f32_e32 v213, v29, v221
	v_fmac_f32_e32 v214, v30, v222
	v_fmac_f32_e32 v215, v31, v223

.Lact_t2_k5:
	s_mov_b64 exec, s[38:39]
	v_mul_f32_e32 v216, v208, v208
	v_mul_f32_e32 v217, v209, v209
	v_mul_f32_e32 v218, v210, v210
	v_mul_f32_e32 v219, v211, v211
	v_mul_f32_e32 v220, v212, v212
	v_mul_f32_e32 v221, v213, v213
	v_mul_f32_e32 v222, v214, v214
	v_mul_f32_e32 v223, v215, v215
	v_fmamk_f32 v216, v216, 0x3dd2d3e8, v204
	v_fmamk_f32 v217, v217, 0x3dd2d3e8, v204
	v_fmamk_f32 v218, v218, 0x3dd2d3e8, v204
	v_fmamk_f32 v219, v219, 0x3dd2d3e8, v204
	v_fmamk_f32 v220, v220, 0x3dd2d3e8, v204
	v_fmamk_f32 v221, v221, 0x3dd2d3e8, v204
	v_fmamk_f32 v222, v222, 0x3dd2d3e8, v204
	v_fmamk_f32 v223, v223, 0x3dd2d3e8, v204
	v_mul_f32_e32 v216, v216, v208
	v_mul_f32_e32 v217, v217, v209
	v_mul_f32_e32 v218, v218, v210
	v_mul_f32_e32 v219, v219, v211
	v_mul_f32_e32 v220, v220, v212
	v_mul_f32_e32 v221, v221, v213
	v_mul_f32_e32 v222, v222, v214
	v_mul_f32_e32 v223, v223, v215
	v_exp_f32_e32 v216, v216
	v_exp_f32_e32 v217, v217
	v_exp_f32_e32 v218, v218
	v_exp_f32_e32 v219, v219
	v_exp_f32_e32 v220, v220
	v_exp_f32_e32 v221, v221
	v_exp_f32_e32 v222, v222
	v_exp_f32_e32 v223, v223
	v_lshlrev_b32_e32 v224, 16, v156
	v_and_b32_e32 v225, 0xffff0000, v156
	v_lshlrev_b32_e32 v226, 16, v157
	v_and_b32_e32 v227, 0xffff0000, v157
	v_lshlrev_b32_e32 v228, 16, v158
	v_and_b32_e32 v229, 0xffff0000, v158
	v_lshlrev_b32_e32 v230, 16, v159
	v_and_b32_e32 v231, 0xffff0000, v159
	v_add_f32_e32 v216, 1.0, v216
	v_add_f32_e32 v217, 1.0, v217
	v_add_f32_e32 v218, 1.0, v218
	v_add_f32_e32 v219, 1.0, v219
	v_add_f32_e32 v220, 1.0, v220
	v_add_f32_e32 v221, 1.0, v221
	v_add_f32_e32 v222, 1.0, v222
	v_add_f32_e32 v223, 1.0, v223
	v_rcp_f32_e32 v216, v216
	v_rcp_f32_e32 v217, v217
	v_rcp_f32_e32 v218, v218
	v_rcp_f32_e32 v219, v219
	v_rcp_f32_e32 v220, v220
	v_rcp_f32_e32 v221, v221
	v_rcp_f32_e32 v222, v222
	v_rcp_f32_e32 v223, v223
	s_nop 0
	v_fma_f32 v216, -v208, v216, v208
	v_fma_f32 v217, -v209, v217, v209
	v_fma_f32 v218, -v210, v218, v210
	v_fma_f32 v219, -v211, v219, v211
	v_fma_f32 v220, -v212, v220, v212
	v_fma_f32 v221, -v213, v221, v213
	v_fma_f32 v222, -v214, v222, v214
	v_fma_f32 v223, -v215, v223, v215
	v_mul_f32_e32 v216, v216, v224
	v_mul_f32_e32 v217, v217, v225
	v_mul_f32_e32 v218, v218, v226
	v_mul_f32_e32 v219, v219, v227
	v_mul_f32_e32 v220, v220, v228
	v_mul_f32_e32 v221, v221, v229
	v_mul_f32_e32 v222, v222, v230
	v_mul_f32_e32 v223, v223, v231
	v_cvt_pk_bf16_f32 v208, v216, v217
	v_cvt_pk_bf16_f32 v209, v218, v219
	v_cvt_pk_bf16_f32 v210, v220, v221
	v_cvt_pk_bf16_f32 v211, v222, v223
	global_store_dwordx4 v198, v[208:211], s[96:97] sc1
	v_and_b32_e32 v200, 0xff, v172
	v_mad_u32_u24 v198, v172, s15, v199
	v_cmp_ne_u32_e64 s[50:51], 0, v200
	v_cmp_ne_u32_e64 s[52:53], s16, v200
	global_load_dwordx4 v[132:135], v198, s[60:61]
	global_load_dwordx4 v[156:159], v198, s[96:97] nt
	v_subrev_u32_e32 v201, 0x1600, v198
	v_add_u32_e32 v202, 0x1600, v198
	v_cndmask_b32_e64 v201, v198, v201, s[50:51]
	v_cndmask_b32_e64 v202, v198, v202, s[52:53]
	global_load_dwordx4 v[128:131], v201, s[60:61]
	global_load_dwordx4 v[136:139], v202, s[60:61]
	v_add_u32_e32 v172, s12, v172
	s_waitcnt vmcnt(5)
	v_lshlrev_b32_e32 v216, 16, v96
	v_and_b32_e32 v217, 0xffff0000, v96
	v_lshlrev_b32_e32 v218, 16, v97
	v_and_b32_e32 v219, 0xffff0000, v97
	v_lshlrev_b32_e32 v220, 16, v98
	v_and_b32_e32 v221, 0xffff0000, v98
	v_lshlrev_b32_e32 v222, 16, v99
	v_and_b32_e32 v223, 0xffff0000, v99
	v_fma_f32 v208, v32, v216, v72
	v_fma_f32 v209, v33, v217, v73
	v_fma_f32 v210, v34, v218, v74
	v_fma_f32 v211, v35, v219, v75
	v_fma_f32 v212, v36, v220, v76
	v_fma_f32 v213, v37, v221, v77
	v_fma_f32 v214, v38, v222, v78
	v_fma_f32 v215, v39, v223, v79
	s_mov_b64 exec, s[86:87]
	s_cbranch_execz .Lact_t3_k3
	v_lshlrev_b32_e32 v216, 16, v92
	v_and_b32_e32 v217, 0xffff0000, v92
	v_lshlrev_b32_e32 v218, 16, v93
	v_and_b32_e32 v219, 0xffff0000, v93
	v_lshlrev_b32_e32 v220, 16, v94
	v_and_b32_e32 v221, 0xffff0000, v94
	v_lshlrev_b32_e32 v222, 16, v95
	v_and_b32_e32 v223, 0xffff0000, v95
	v_fmac_f32_e32 v208, v24, v216
	v_fmac_f32_e32 v209, v25, v217
	v_fmac_f32_e32 v210, v26, v218
	v_fmac_f32_e32 v211, v27, v219
	v_fmac_f32_e32 v212, v28, v220
	v_fmac_f32_e32 v213, v29, v221
	v_fmac_f32_e32 v214, v30, v222
	v_fmac_f32_e32 v215, v31, v223

.Lact_t4_k5:
	s_mov_b64 exec, s[38:39]
	v_mul_f32_e32 v216, v208, v208
	v_mul_f32_e32 v217, v209, v209
	v_mul_f32_e32 v218, v210, v210
	v_mul_f32_e32 v219, v211, v211
	v_mul_f32_e32 v220, v212, v212
	v_mul_f32_e32 v221, v213, v213
	v_mul_f32_e32 v222, v214, v214
	v_mul_f32_e32 v223, v215, v215
	v_fmamk_f32 v216, v216, 0x3dd2d3e8, v204
	v_fmamk_f32 v217, v217, 0x3dd2d3e8, v204
	v_fmamk_f32 v218, v218, 0x3dd2d3e8, v204
	v_fmamk_f32 v219, v219, 0x3dd2d3e8, v204
	v_fmamk_f32 v220, v220, 0x3dd2d3e8, v204
	v_fmamk_f32 v221, v221, 0x3dd2d3e8, v204
	v_fmamk_f32 v222, v222, 0x3dd2d3e8, v204
	v_fmamk_f32 v223, v223, 0x3dd2d3e8, v204
	v_mul_f32_e32 v216, v216, v208
	v_mul_f32_e32 v217, v217, v209
	v_mul_f32_e32 v218, v218, v210
	v_mul_f32_e32 v219, v219, v211
	v_mul_f32_e32 v220, v220, v212
	v_mul_f32_e32 v221, v221, v213
	v_mul_f32_e32 v222, v222, v214
	v_mul_f32_e32 v223, v223, v215
	v_exp_f32_e32 v216, v216
	v_exp_f32_e32 v217, v217
	v_exp_f32_e32 v218, v218
	v_exp_f32_e32 v219, v219
	v_exp_f32_e32 v220, v220
	v_exp_f32_e32 v221, v221
	v_exp_f32_e32 v222, v222
	v_exp_f32_e32 v223, v223
	v_lshlrev_b32_e32 v224, 16, v156
	v_and_b32_e32 v225, 0xffff0000, v156
	v_lshlrev_b32_e32 v226, 16, v157
	v_and_b32_e32 v227, 0xffff0000, v157
	v_lshlrev_b32_e32 v228, 16, v158
	v_and_b32_e32 v229, 0xffff0000, v158
	v_lshlrev_b32_e32 v230, 16, v159
	v_and_b32_e32 v231, 0xffff0000, v159
	v_add_f32_e32 v216, 1.0, v216
	v_add_f32_e32 v217, 1.0, v217
	v_add_f32_e32 v218, 1.0, v218
	v_add_f32_e32 v219, 1.0, v219
	v_add_f32_e32 v220, 1.0, v220
	v_add_f32_e32 v221, 1.0, v221
	v_add_f32_e32 v222, 1.0, v222
	v_add_f32_e32 v223, 1.0, v223
	v_rcp_f32_e32 v216, v216
	v_rcp_f32_e32 v217, v217
	v_rcp_f32_e32 v218, v218
	v_rcp_f32_e32 v219, v219
	v_rcp_f32_e32 v220, v220
	v_rcp_f32_e32 v221, v221
	v_rcp_f32_e32 v222, v222
	v_rcp_f32_e32 v223, v223
	s_nop 0
	v_fma_f32 v216, -v208, v216, v208
	v_fma_f32 v217, -v209, v217, v209
	v_fma_f32 v218, -v210, v218, v210
	v_fma_f32 v219, -v211, v219, v211
	v_fma_f32 v220, -v212, v220, v212
	v_fma_f32 v221, -v213, v221, v213
	v_fma_f32 v222, -v214, v222, v214
	v_fma_f32 v223, -v215, v223, v215
	v_mul_f32_e32 v216, v216, v224
	v_mul_f32_e32 v217, v217, v225
	v_mul_f32_e32 v218, v218, v226
	v_mul_f32_e32 v219, v219, v227
	v_mul_f32_e32 v220, v220, v228
	v_mul_f32_e32 v221, v221, v229
	v_mul_f32_e32 v222, v222, v230
	v_mul_f32_e32 v223, v223, v231
	v_cvt_pk_bf16_f32 v208, v216, v217
	v_cvt_pk_bf16_f32 v209, v218, v219
	v_cvt_pk_bf16_f32 v210, v220, v221
	v_cvt_pk_bf16_f32 v211, v222, v223
	global_store_dwordx4 v198, v[208:211], s[96:97] sc1
	v_mov_b32_e32 v195, v172
	v_and_b32_e32 v200, 56, v195
	v_lshrrev_b32_e32 v201, 3, v195
	v_and_b32_e32 v201, 56, v201
	v_lshl_or_b32 v200, v200, 3, v201
	v_and_b32_e32 v201, 0xfffffe07, v195
	v_or_b32_e32 v200, v200, v201
	v_cmp_lt_i32_e32 vcc, s14, v195
	s_nop 1
	v_cndmask_b32_e32 v195, v195, v200, vcc
	v_and_b32_e32 v200, 63, v195
	v_bfe_u32 v201, v195, 6, 6
	v_and_b32_e32 v202, 0xff, v195
	v_mov_b32_e32 v216, 0xff
	v_cndmask_b32_e32 v200, v202, v200, vcc
	v_cndmask_b32_e64 v216, v216, 63, vcc
	s_mov_b64 s[0:1], vcc
	v_cmp_ne_u32_e64 s[86:87], 0, v200
	v_cmp_ne_u32_e64 s[88:89], v216, v200
	v_cmp_ne_u32_e64 s[82:83], 0, v201
	v_cmp_ne_u32_e64 s[92:93], 63, v201
	v_mad_u32_u24 v197, v195, s15, v199
	s_and_b64 s[82:83], s[82:83], s[0:1]
	s_and_b64 s[92:93], s[92:93], s[0:1]
	s_and_b64 s[80:81], s[82:83], s[86:87]
	s_and_b64 s[84:85], s[82:83], s[88:89]
	s_and_b64 s[90:91], s[92:93], s[86:87]
	s_and_b64 s[94:95], s[92:93], s[88:89]
	global_load_dwordx4 v[96:99], v197, s[60:61]
	global_load_dwordx4 v[152:155], v197, s[96:97] nt
	v_subrev_u32_e32 v217, 0x59600, v197
	v_subrev_u32_e32 v218, 0x58000, v197
	v_subrev_u32_e32 v219, 0x56a00, v197
	v_subrev_u32_e32 v220, 0x1600, v197
	v_add_u32_e32 v221, 0x1600, v197
	v_add_u32_e32 v222, 0x56a00, v197
	v_add_u32_e32 v223, 0x58000, v197
	v_add_u32_e32 v224, 0x59600, v197
	s_nop 0
	v_cndmask_b32_e64 v217, v197, v217, s[80:81]
	v_cndmask_b32_e64 v218, v197, v218, s[82:83]
	v_cndmask_b32_e64 v219, v197, v219, s[84:85]
	v_cndmask_b32_e64 v220, v197, v220, s[86:87]
	v_cndmask_b32_e64 v221, v197, v221, s[88:89]
	v_cndmask_b32_e64 v222, v197, v222, s[90:91]
	v_cndmask_b32_e64 v223, v197, v223, s[92:93]
	v_cndmask_b32_e64 v224, v197, v224, s[94:95]
	global_load_dwordx4 v[80:83], v217, s[60:61]
	global_load_dwordx4 v[84:87], v218, s[60:61]
	global_load_dwordx4 v[88:91], v219, s[60:61]
	global_load_dwordx4 v[92:95], v220, s[60:61]
	global_load_dwordx4 v[100:103], v221, s[60:61]
	global_load_dwordx4 v[104:107], v222, s[60:61]
	global_load_dwordx4 v[108:111], v223, s[60:61]
	global_load_dwordx4 v[112:115], v224, s[60:61]
	v_add_u32_e32 v172, s12, v172
	v_mov_b32_e32 v195, v172
	v_and_b32_e32 v200, 56, v195
	v_lshrrev_b32_e32 v201, 3, v195
	v_and_b32_e32 v201, 56, v201
	v_lshl_or_b32 v200, v200, 3, v201
	v_and_b32_e32 v201, 0xfffffe07, v195
	v_or_b32_e32 v200, v200, v201
	v_cmp_lt_i32_e32 vcc, s14, v195
	s_nop 1
	v_cndmask_b32_e32 v195, v195, v200, vcc
	v_and_b32_e32 v200, 63, v195
	v_bfe_u32 v201, v195, 6, 6
	v_and_b32_e32 v202, 0xff, v195
	v_mov_b32_e32 v216, 0xff
	v_cndmask_b32_e32 v200, v202, v200, vcc
	v_cndmask_b32_e64 v216, v216, 63, vcc
	s_mov_b64 s[0:1], vcc
	v_cmp_ne_u32_e64 s[50:51], 0, v200
	v_cmp_ne_u32_e64 s[52:53], v216, v200
	v_cmp_ne_u32_e64 s[46:47], 0, v201
	v_cmp_ne_u32_e64 s[56:57], 63, v201
	v_mad_u32_u24 v198, v195, s15, v199
	s_and_b64 s[46:47], s[46:47], s[0:1]
	s_and_b64 s[56:57], s[56:57], s[0:1]
	s_and_b64 s[44:45], s[46:47], s[50:51]
	s_and_b64 s[48:49], s[46:47], s[52:53]
	s_and_b64 s[54:55], s[56:57], s[50:51]
	s_and_b64 s[58:59], s[56:57], s[52:53]
	global_load_dwordx4 v[132:135], v198, s[60:61]
	global_load_dwordx4 v[156:159], v198, s[96:97] nt
	v_subrev_u32_e32 v217, 0x59600, v198
	v_subrev_u32_e32 v218, 0x58000, v198
	v_subrev_u32_e32 v219, 0x56a00, v198
	v_subrev_u32_e32 v220, 0x1600, v198
	v_add_u32_e32 v221, 0x1600, v198
	v_add_u32_e32 v222, 0x56a00, v198
	v_add_u32_e32 v223, 0x58000, v198
	v_add_u32_e32 v224, 0x59600, v198
	s_nop 0
	v_cndmask_b32_e64 v217, v198, v217, s[44:45]
	v_cndmask_b32_e64 v218, v198, v218, s[46:47]
	v_cndmask_b32_e64 v219, v198, v219, s[48:49]
	v_cndmask_b32_e64 v220, v198, v220, s[50:51]
	v_cndmask_b32_e64 v221, v198, v221, s[52:53]
	v_cndmask_b32_e64 v222, v198, v222, s[54:55]
	v_cndmask_b32_e64 v223, v198, v223, s[56:57]
	v_cndmask_b32_e64 v224, v198, v224, s[58:59]
	global_load_dwordx4 v[116:119], v217, s[60:61]
	global_load_dwordx4 v[120:123], v218, s[60:61]
	global_load_dwordx4 v[124:127], v219, s[60:61]
	global_load_dwordx4 v[128:131], v220, s[60:61]
	global_load_dwordx4 v[136:139], v221, s[60:61]
	global_load_dwordx4 v[140:143], v222, s[60:61]
	global_load_dwordx4 v[144:147], v223, s[60:61]
	global_load_dwordx4 v[148:151], v224, s[60:61]
	v_add_u32_e32 v172, s12, v172
	s_waitcnt vmcnt(10)
	v_lshlrev_b32_e32 v216, 16, v96
	v_and_b32_e32 v217, 0xffff0000, v96
	v_lshlrev_b32_e32 v218, 16, v97
	v_and_b32_e32 v219, 0xffff0000, v97
	v_lshlrev_b32_e32 v220, 16, v98
	v_and_b32_e32 v221, 0xffff0000, v98
	v_lshlrev_b32_e32 v222, 16, v99
	v_and_b32_e32 v223, 0xffff0000, v99
	v_fma_f32 v208, v32, v216, v72
	v_fma_f32 v209, v33, v217, v73
	v_fma_f32 v210, v34, v218, v74
	v_fma_f32 v211, v35, v219, v75
	v_fma_f32 v212, v36, v220, v76
	v_fma_f32 v213, v37, v221, v77
	v_fma_f32 v214, v38, v222, v78
	v_fma_f32 v215, v39, v223, v79
	s_mov_b64 exec, s[80:81]
	s_cbranch_execz .Lact_t5_k0
	v_lshlrev_b32_e32 v216, 16, v80
	v_and_b32_e32 v217, 0xffff0000, v80
	v_lshlrev_b32_e32 v218, 16, v81
	v_and_b32_e32 v219, 0xffff0000, v81
	v_lshlrev_b32_e32 v220, 16, v82
	v_and_b32_e32 v221, 0xffff0000, v82
	v_lshlrev_b32_e32 v222, 16, v83
	v_and_b32_e32 v223, 0xffff0000, v83
	v_fmac_f32_e32 v208, v0, v216
	v_fmac_f32_e32 v209, v1, v217
	v_fmac_f32_e32 v210, v2, v218
	v_fmac_f32_e32 v211, v3, v219
	v_fmac_f32_e32 v212, v4, v220
	v_fmac_f32_e32 v213, v5, v221
	v_fmac_f32_e32 v214, v6, v222
	v_fmac_f32_e32 v215, v7, v223

.Lact_lat_loop:
	v_mov_b32_e32 v195, v172
	v_and_b32_e32 v200, 56, v195
	v_lshrrev_b32_e32 v201, 3, v195
	v_and_b32_e32 v201, 56, v201
	v_lshl_or_b32 v200, v200, 3, v201
	v_and_b32_e32 v201, 0xfffffe07, v195
	v_or_b32_e32 v200, v200, v201
	v_cmp_lt_i32_e32 vcc, s14, v195
	s_nop 1
	v_cndmask_b32_e32 v195, v195, v200, vcc
	v_and_b32_e32 v200, 63, v195
	v_bfe_u32 v201, v195, 6, 6
	v_and_b32_e32 v202, 0xff, v195
	v_mov_b32_e32 v216, 0xff
	v_cndmask_b32_e32 v200, v202, v200, vcc
	v_cndmask_b32_e64 v216, v216, 63, vcc
	s_mov_b64 s[0:1], vcc
	v_cmp_ne_u32_e64 s[86:87], 0, v200
	v_cmp_ne_u32_e64 s[88:89], v216, v200
	v_cmp_ne_u32_e64 s[82:83], 0, v201
	v_cmp_ne_u32_e64 s[92:93], 63, v201
	v_mad_u32_u24 v197, v195, s15, v199
	s_and_b64 s[82:83], s[82:83], s[0:1]
	s_and_b64 s[92:93], s[92:93], s[0:1]
	s_and_b64 s[80:81], s[82:83], s[86:87]
	s_and_b64 s[84:85], s[82:83], s[88:89]
	s_and_b64 s[90:91], s[92:93], s[86:87]
	s_and_b64 s[94:95], s[92:93], s[88:89]
	global_load_dwordx4 v[96:99], v197, s[60:61]
	global_load_dwordx4 v[152:155], v197, s[96:97] nt
	v_subrev_u32_e32 v217, 0x59600, v197
	v_subrev_u32_e32 v218, 0x58000, v197
	v_subrev_u32_e32 v219, 0x56a00, v197
	v_subrev_u32_e32 v220, 0x1600, v197
	v_add_u32_e32 v221, 0x1600, v197
	v_add_u32_e32 v222, 0x56a00, v197
	v_add_u32_e32 v223, 0x58000, v197
	v_add_u32_e32 v224, 0x59600, v197
	s_nop 0
	v_cndmask_b32_e64 v217, v197, v217, s[80:81]
	v_cndmask_b32_e64 v218, v197, v218, s[82:83]
	v_cndmask_b32_e64 v219, v197, v219, s[84:85]
	v_cndmask_b32_e64 v220, v197, v220, s[86:87]
	v_cndmask_b32_e64 v221, v197, v221, s[88:89]
	v_cndmask_b32_e64 v222, v197, v222, s[90:91]
	v_cndmask_b32_e64 v223, v197, v223, s[92:93]
	v_cndmask_b32_e64 v224, v197, v224, s[94:95]
	global_load_dwordx4 v[80:83], v217, s[60:61]
	global_load_dwordx4 v[84:87], v218, s[60:61]
	global_load_dwordx4 v[88:91], v219, s[60:61]
	global_load_dwordx4 v[92:95], v220, s[60:61]
	global_load_dwordx4 v[100:103], v221, s[60:61]
	global_load_dwordx4 v[104:107], v222, s[60:61]
	global_load_dwordx4 v[108:111], v223, s[60:61]
	global_load_dwordx4 v[112:115], v224, s[60:61]
	v_add_u32_e32 v172, s12, v172
	s_waitcnt vmcnt(11)
	v_lshlrev_b32_e32 v216, 16, v132
	v_and_b32_e32 v217, 0xffff0000, v132
	v_lshlrev_b32_e32 v218, 16, v133
	v_and_b32_e32 v219, 0xffff0000, v133
	v_lshlrev_b32_e32 v220, 16, v134
	v_and_b32_e32 v221, 0xffff0000, v134
	v_lshlrev_b32_e32 v222, 16, v135
	v_and_b32_e32 v223, 0xffff0000, v135
	v_fma_f32 v208, v32, v216, v72
	v_fma_f32 v209, v33, v217, v73
	v_fma_f32 v210, v34, v218, v74
	v_fma_f32 v211, v35, v219, v75
	v_fma_f32 v212, v36, v220, v76
	v_fma_f32 v213, v37, v221, v77
	v_fma_f32 v214, v38, v222, v78
	v_fma_f32 v215, v39, v223, v79
	s_mov_b64 exec, s[44:45]
	s_cbranch_execz .Lact_t6_k0
	v_lshlrev_b32_e32 v216, 16, v116
	v_and_b32_e32 v217, 0xffff0000, v116
	v_lshlrev_b32_e32 v218, 16, v117
	v_and_b32_e32 v219, 0xffff0000, v117
	v_lshlrev_b32_e32 v220, 16, v118
	v_and_b32_e32 v221, 0xffff0000, v118
	v_lshlrev_b32_e32 v222, 16, v119
	v_and_b32_e32 v223, 0xffff0000, v119
	v_fmac_f32_e32 v208, v0, v216
	v_fmac_f32_e32 v209, v1, v217
	v_fmac_f32_e32 v210, v2, v218
	v_fmac_f32_e32 v211, v3, v219
	v_fmac_f32_e32 v212, v4, v220
	v_fmac_f32_e32 v213, v5, v221
	v_fmac_f32_e32 v214, v6, v222
	v_fmac_f32_e32 v215, v7, v223

.Lact_t6_k8:
	s_mov_b64 exec, s[38:39]
	v_mul_f32_e32 v216, v208, v208
	v_mul_f32_e32 v217, v209, v209
	v_mul_f32_e32 v218, v210, v210
	v_mul_f32_e32 v219, v211, v211
	v_mul_f32_e32 v220, v212, v212
	v_mul_f32_e32 v221, v213, v213
	v_mul_f32_e32 v222, v214, v214
	v_mul_f32_e32 v223, v215, v215
	v_fmamk_f32 v216, v216, 0x3dd2d3e8, v204
	v_fmamk_f32 v217, v217, 0x3dd2d3e8, v204
	v_fmamk_f32 v218, v218, 0x3dd2d3e8, v204
	v_fmamk_f32 v219, v219, 0x3dd2d3e8, v204
	v_fmamk_f32 v220, v220, 0x3dd2d3e8, v204
	v_fmamk_f32 v221, v221, 0x3dd2d3e8, v204
	v_fmamk_f32 v222, v222, 0x3dd2d3e8, v204
	v_fmamk_f32 v223, v223, 0x3dd2d3e8, v204
	v_mul_f32_e32 v216, v216, v208
	v_mul_f32_e32 v217, v217, v209
	v_mul_f32_e32 v218, v218, v210
	v_mul_f32_e32 v219, v219, v211
	v_mul_f32_e32 v220, v220, v212
	v_mul_f32_e32 v221, v221, v213
	v_mul_f32_e32 v222, v222, v214
	v_mul_f32_e32 v223, v223, v215
	v_exp_f32_e32 v216, v216
	v_exp_f32_e32 v217, v217
	v_exp_f32_e32 v218, v218
	v_exp_f32_e32 v219, v219
	v_exp_f32_e32 v220, v220
	v_exp_f32_e32 v221, v221
	v_exp_f32_e32 v222, v222
	v_exp_f32_e32 v223, v223
	v_lshlrev_b32_e32 v224, 16, v156
	v_and_b32_e32 v225, 0xffff0000, v156
	v_lshlrev_b32_e32 v226, 16, v157
	v_and_b32_e32 v227, 0xffff0000, v157
	v_lshlrev_b32_e32 v228, 16, v158
	v_and_b32_e32 v229, 0xffff0000, v158
	v_lshlrev_b32_e32 v230, 16, v159
	v_and_b32_e32 v231, 0xffff0000, v159
	v_add_f32_e32 v216, 1.0, v216
	v_add_f32_e32 v217, 1.0, v217
	v_add_f32_e32 v218, 1.0, v218
	v_add_f32_e32 v219, 1.0, v219
	v_add_f32_e32 v220, 1.0, v220
	v_add_f32_e32 v221, 1.0, v221
	v_add_f32_e32 v222, 1.0, v222
	v_add_f32_e32 v223, 1.0, v223
	v_rcp_f32_e32 v216, v216
	v_rcp_f32_e32 v217, v217
	v_rcp_f32_e32 v218, v218
	v_rcp_f32_e32 v219, v219
	v_rcp_f32_e32 v220, v220
	v_rcp_f32_e32 v221, v221
	v_rcp_f32_e32 v222, v222
	v_rcp_f32_e32 v223, v223
	s_nop 0
	v_fma_f32 v216, -v208, v216, v208
	v_fma_f32 v217, -v209, v217, v209
	v_fma_f32 v218, -v210, v218, v210
	v_fma_f32 v219, -v211, v219, v211
	v_fma_f32 v220, -v212, v220, v212
	v_fma_f32 v221, -v213, v221, v213
	v_fma_f32 v222, -v214, v222, v214
	v_fma_f32 v223, -v215, v223, v215
	v_mul_f32_e32 v216, v216, v224
	v_mul_f32_e32 v217, v217, v225
	v_mul_f32_e32 v218, v218, v226
	v_mul_f32_e32 v219, v219, v227
	v_mul_f32_e32 v220, v220, v228
	v_mul_f32_e32 v221, v221, v229
	v_mul_f32_e32 v222, v222, v230
	v_mul_f32_e32 v223, v223, v231
	v_cvt_pk_bf16_f32 v208, v216, v217
	v_cvt_pk_bf16_f32 v209, v218, v219
	v_cvt_pk_bf16_f32 v210, v220, v221
	v_cvt_pk_bf16_f32 v211, v222, v223
	global_store_dwordx4 v198, v[208:211], s[96:97] sc1
	v_mov_b32_e32 v195, v172
	v_and_b32_e32 v200, 56, v195
	v_lshrrev_b32_e32 v201, 3, v195
	v_and_b32_e32 v201, 56, v201
	v_lshl_or_b32 v200, v200, 3, v201
	v_and_b32_e32 v201, 0xfffffe07, v195
	v_or_b32_e32 v200, v200, v201
	v_cmp_lt_i32_e32 vcc, s14, v195
	s_nop 1
	v_cndmask_b32_e32 v195, v195, v200, vcc
	v_and_b32_e32 v200, 63, v195
	v_bfe_u32 v201, v195, 6, 6
	v_and_b32_e32 v202, 0xff, v195
	v_mov_b32_e32 v216, 0xff
	v_cndmask_b32_e32 v200, v202, v200, vcc
	v_cndmask_b32_e64 v216, v216, 63, vcc
	s_mov_b64 s[0:1], vcc
	v_cmp_ne_u32_e64 s[50:51], 0, v200
	v_cmp_ne_u32_e64 s[52:53], v216, v200
	v_cmp_ne_u32_e64 s[46:47], 0, v201
	v_cmp_ne_u32_e64 s[56:57], 63, v201
	v_mad_u32_u24 v198, v195, s15, v199
	s_and_b64 s[46:47], s[46:47], s[0:1]
	s_and_b64 s[56:57], s[56:57], s[0:1]
	s_and_b64 s[44:45], s[46:47], s[50:51]
	s_and_b64 s[48:49], s[46:47], s[52:53]
	s_and_b64 s[54:55], s[56:57], s[50:51]
	s_and_b64 s[58:59], s[56:57], s[52:53]
	global_load_dwordx4 v[132:135], v198, s[60:61]
	global_load_dwordx4 v[156:159], v198, s[96:97] nt
	v_subrev_u32_e32 v217, 0x59600, v198
	v_subrev_u32_e32 v218, 0x58000, v198
	v_subrev_u32_e32 v219, 0x56a00, v198
	v_subrev_u32_e32 v220, 0x1600, v198
	v_add_u32_e32 v221, 0x1600, v198
	v_add_u32_e32 v222, 0x56a00, v198
	v_add_u32_e32 v223, 0x58000, v198
	v_add_u32_e32 v224, 0x59600, v198
	s_nop 0
	v_cndmask_b32_e64 v217, v198, v217, s[44:45]
	v_cndmask_b32_e64 v218, v198, v218, s[46:47]
	v_cndmask_b32_e64 v219, v198, v219, s[48:49]
	v_cndmask_b32_e64 v220, v198, v220, s[50:51]
	v_cndmask_b32_e64 v221, v198, v221, s[52:53]
	v_cndmask_b32_e64 v222, v198, v222, s[54:55]
	v_cndmask_b32_e64 v223, v198, v223, s[56:57]
	v_cndmask_b32_e64 v224, v198, v224, s[58:59]
	global_load_dwordx4 v[116:119], v217, s[60:61]
	global_load_dwordx4 v[120:123], v218, s[60:61]
	global_load_dwordx4 v[124:127], v219, s[60:61]
	global_load_dwordx4 v[128:131], v220, s[60:61]
	global_load_dwordx4 v[136:139], v221, s[60:61]
	global_load_dwordx4 v[140:143], v222, s[60:61]
	global_load_dwordx4 v[144:147], v223, s[60:61]
	global_load_dwordx4 v[148:151], v224, s[60:61]
	v_add_u32_e32 v172, s12, v172
	s_waitcnt vmcnt(11)
	v_lshlrev_b32_e32 v216, 16, v96
	v_and_b32_e32 v217, 0xffff0000, v96
	v_lshlrev_b32_e32 v218, 16, v97
	v_and_b32_e32 v219, 0xffff0000, v97
	v_lshlrev_b32_e32 v220, 16, v98
	v_and_b32_e32 v221, 0xffff0000, v98
	v_lshlrev_b32_e32 v222, 16, v99
	v_and_b32_e32 v223, 0xffff0000, v99
	v_fma_f32 v208, v32, v216, v72
	v_fma_f32 v209, v33, v217, v73
	v_fma_f32 v210, v34, v218, v74
	v_fma_f32 v211, v35, v219, v75
	v_fma_f32 v212, v36, v220, v76
	v_fma_f32 v213, v37, v221, v77
	v_fma_f32 v214, v38, v222, v78
	v_fma_f32 v215, v39, v223, v79
	s_mov_b64 exec, s[80:81]
	s_cbranch_execz .Lact_t7_k0
	v_lshlrev_b32_e32 v216, 16, v80
	v_and_b32_e32 v217, 0xffff0000, v80
	v_lshlrev_b32_e32 v218, 16, v81
	v_and_b32_e32 v219, 0xffff0000, v81
	v_lshlrev_b32_e32 v220, 16, v82
	v_and_b32_e32 v221, 0xffff0000, v82
	v_lshlrev_b32_e32 v222, 16, v83
	v_and_b32_e32 v223, 0xffff0000, v83
	v_fmac_f32_e32 v208, v0, v216
	v_fmac_f32_e32 v209, v1, v217
	v_fmac_f32_e32 v210, v2, v218
	v_fmac_f32_e32 v211, v3, v219
	v_fmac_f32_e32 v212, v4, v220
	v_fmac_f32_e32 v213, v5, v221
	v_fmac_f32_e32 v214, v6, v222
	v_fmac_f32_e32 v215, v7, v223

.Lact_t8_k8:
	s_mov_b64 exec, s[38:39]
	v_mul_f32_e32 v216, v208, v208
	v_mul_f32_e32 v217, v209, v209
	v_mul_f32_e32 v218, v210, v210
	v_mul_f32_e32 v219, v211, v211
	v_mul_f32_e32 v220, v212, v212
	v_mul_f32_e32 v221, v213, v213
	v_mul_f32_e32 v222, v214, v214
	v_mul_f32_e32 v223, v215, v215
	v_fmamk_f32 v216, v216, 0x3dd2d3e8, v204
	v_fmamk_f32 v217, v217, 0x3dd2d3e8, v204
	v_fmamk_f32 v218, v218, 0x3dd2d3e8, v204
	v_fmamk_f32 v219, v219, 0x3dd2d3e8, v204
	v_fmamk_f32 v220, v220, 0x3dd2d3e8, v204
	v_fmamk_f32 v221, v221, 0x3dd2d3e8, v204
	v_fmamk_f32 v222, v222, 0x3dd2d3e8, v204
	v_fmamk_f32 v223, v223, 0x3dd2d3e8, v204
	v_mul_f32_e32 v216, v216, v208
	v_mul_f32_e32 v217, v217, v209
	v_mul_f32_e32 v218, v218, v210
	v_mul_f32_e32 v219, v219, v211
	v_mul_f32_e32 v220, v220, v212
	v_mul_f32_e32 v221, v221, v213
	v_mul_f32_e32 v222, v222, v214
	v_mul_f32_e32 v223, v223, v215
	v_exp_f32_e32 v216, v216
	v_exp_f32_e32 v217, v217
	v_exp_f32_e32 v218, v218
	v_exp_f32_e32 v219, v219
	v_exp_f32_e32 v220, v220
	v_exp_f32_e32 v221, v221
	v_exp_f32_e32 v222, v222
	v_exp_f32_e32 v223, v223
	v_lshlrev_b32_e32 v224, 16, v156
	v_and_b32_e32 v225, 0xffff0000, v156
	v_lshlrev_b32_e32 v226, 16, v157
	v_and_b32_e32 v227, 0xffff0000, v157
	v_lshlrev_b32_e32 v228, 16, v158
	v_and_b32_e32 v229, 0xffff0000, v158
	v_lshlrev_b32_e32 v230, 16, v159
	v_and_b32_e32 v231, 0xffff0000, v159
	v_add_f32_e32 v216, 1.0, v216
	v_add_f32_e32 v217, 1.0, v217
	v_add_f32_e32 v218, 1.0, v218
	v_add_f32_e32 v219, 1.0, v219
	v_add_f32_e32 v220, 1.0, v220
	v_add_f32_e32 v221, 1.0, v221
	v_add_f32_e32 v222, 1.0, v222
	v_add_f32_e32 v223, 1.0, v223
	v_rcp_f32_e32 v216, v216
	v_rcp_f32_e32 v217, v217
	v_rcp_f32_e32 v218, v218
	v_rcp_f32_e32 v219, v219
	v_rcp_f32_e32 v220, v220
	v_rcp_f32_e32 v221, v221
	v_rcp_f32_e32 v222, v222
	v_rcp_f32_e32 v223, v223
	s_nop 0
	v_fma_f32 v216, -v208, v216, v208
	v_fma_f32 v217, -v209, v217, v209
	v_fma_f32 v218, -v210, v218, v210
	v_fma_f32 v219, -v211, v219, v211
	v_fma_f32 v220, -v212, v220, v212
	v_fma_f32 v221, -v213, v221, v213
	v_fma_f32 v222, -v214, v222, v214
	v_fma_f32 v223, -v215, v223, v215
	v_mul_f32_e32 v216, v216, v224
	v_mul_f32_e32 v217, v217, v225
	v_mul_f32_e32 v218, v218, v226
	v_mul_f32_e32 v219, v219, v227
	v_mul_f32_e32 v220, v220, v228
	v_mul_f32_e32 v221, v221, v229
	v_mul_f32_e32 v222, v222, v230
	v_mul_f32_e32 v223, v223, v231
	v_cvt_pk_bf16_f32 v208, v216, v217
	v_cvt_pk_bf16_f32 v209, v218, v219
	v_cvt_pk_bf16_f32 v210, v220, v221
	v_cvt_pk_bf16_f32 v211, v222, v223
	global_store_dwordx4 v198, v[208:211], s[96:97] sc1
	v_cmp_gt_i32_e32 vcc, s13, v172
	s_and_b64 exec, exec, vcc
	s_cbranch_execz .Lact_done
	s_mov_b64 s[38:39], exec
	v_mov_b32_e32 v195, v172
	v_and_b32_e32 v200, 56, v195
	v_lshrrev_b32_e32 v201, 3, v195
	v_and_b32_e32 v201, 56, v201
	v_lshl_or_b32 v200, v200, 3, v201
	v_and_b32_e32 v201, 0xfffffe07, v195
	v_or_b32_e32 v200, v200, v201
	v_cmp_lt_i32_e32 vcc, s14, v195
	s_nop 1
	v_cndmask_b32_e32 v195, v195, v200, vcc
	v_and_b32_e32 v200, 63, v195
	v_bfe_u32 v201, v195, 6, 6
	v_and_b32_e32 v202, 0xff, v195
	v_mov_b32_e32 v216, 0xff
	v_cndmask_b32_e32 v200, v202, v200, vcc
	v_cndmask_b32_e64 v216, v216, 63, vcc
	s_mov_b64 s[0:1], vcc
	v_cmp_ne_u32_e64 s[86:87], 0, v200
	v_cmp_ne_u32_e64 s[88:89], v216, v200
	v_cmp_ne_u32_e64 s[82:83], 0, v201
	v_cmp_ne_u32_e64 s[92:93], 63, v201
	v_mad_u32_u24 v197, v195, s15, v199
	s_and_b64 s[82:83], s[82:83], s[0:1]
	s_and_b64 s[92:93], s[92:93], s[0:1]
	s_and_b64 s[80:81], s[82:83], s[86:87]
	s_and_b64 s[84:85], s[82:83], s[88:89]
	s_and_b64 s[90:91], s[92:93], s[86:87]
	s_and_b64 s[94:95], s[92:93], s[88:89]
	global_load_dwordx4 v[96:99], v197, s[60:61]
	global_load_dwordx4 v[152:155], v197, s[96:97] nt
	v_subrev_u32_e32 v217, 0x59600, v197
	v_subrev_u32_e32 v218, 0x58000, v197
	v_subrev_u32_e32 v219, 0x56a00, v197
	v_subrev_u32_e32 v220, 0x1600, v197
	v_add_u32_e32 v221, 0x1600, v197
	v_add_u32_e32 v222, 0x56a00, v197
	v_add_u32_e32 v223, 0x58000, v197
	v_add_u32_e32 v224, 0x59600, v197
	s_nop 0
	v_cndmask_b32_e64 v217, v197, v217, s[80:81]
	v_cndmask_b32_e64 v218, v197, v218, s[82:83]
	v_cndmask_b32_e64 v219, v197, v219, s[84:85]
	v_cndmask_b32_e64 v220, v197, v220, s[86:87]
	v_cndmask_b32_e64 v221, v197, v221, s[88:89]
	v_cndmask_b32_e64 v222, v197, v222, s[90:91]
	v_cndmask_b32_e64 v223, v197, v223, s[92:93]
	v_cndmask_b32_e64 v224, v197, v224, s[94:95]
	global_load_dwordx4 v[80:83], v217, s[60:61]
	global_load_dwordx4 v[84:87], v218, s[60:61]
	global_load_dwordx4 v[88:91], v219, s[60:61]
	global_load_dwordx4 v[92:95], v220, s[60:61]
	global_load_dwordx4 v[100:103], v221, s[60:61]
	global_load_dwordx4 v[104:107], v222, s[60:61]
	global_load_dwordx4 v[108:111], v223, s[60:61]
	global_load_dwordx4 v[112:115], v224, s[60:61]
	s_waitcnt vmcnt(0)
	v_lshlrev_b32_e32 v216, 16, v96
	v_and_b32_e32 v217, 0xffff0000, v96
	v_lshlrev_b32_e32 v218, 16, v97
	v_and_b32_e32 v219, 0xffff0000, v97
	v_lshlrev_b32_e32 v220, 16, v98
	v_and_b32_e32 v221, 0xffff0000, v98
	v_lshlrev_b32_e32 v222, 16, v99
	v_and_b32_e32 v223, 0xffff0000, v99
	v_fma_f32 v208, v32, v216, v72
	v_fma_f32 v209, v33, v217, v73
	v_fma_f32 v210, v34, v218, v74
	v_fma_f32 v211, v35, v219, v75
	v_fma_f32 v212, v36, v220, v76
	v_fma_f32 v213, v37, v221, v77
	v_fma_f32 v214, v38, v222, v78
	v_fma_f32 v215, v39, v223, v79
	s_mov_b64 exec, s[80:81]
	s_cbranch_execz .Lact_t9_k0
	v_lshlrev_b32_e32 v216, 16, v80
	v_and_b32_e32 v217, 0xffff0000, v80
	v_lshlrev_b32_e32 v218, 16, v81
	v_and_b32_e32 v219, 0xffff0000, v81
	v_lshlrev_b32_e32 v220, 16, v82
	v_and_b32_e32 v221, 0xffff0000, v82
	v_lshlrev_b32_e32 v222, 16, v83
	v_and_b32_e32 v223, 0xffff0000, v83
	v_fmac_f32_e32 v208, v0, v216
	v_fmac_f32_e32 v209, v1, v217
	v_fmac_f32_e32 v210, v2, v218
	v_fmac_f32_e32 v211, v3, v219
	v_fmac_f32_e32 v212, v4, v220
	v_fmac_f32_e32 v213, v5, v221
	v_fmac_f32_e32 v214, v6, v222
	v_fmac_f32_e32 v215, v7, v223

.Lfz_nosync:
	s_barrier
	s_and_b32 s9, s72, 7
	s_lshl_b32 s9, s9, 3
	s_bfe_u32 s11, s72, 0x30003
	s_or_b32 s9, s9, s11
	s_lshr_b32 s10, s72, 6
	v_and_b32_e32 v234, 15, v233
	v_lshrrev_b32_e32 v235, 4, v233
	s_and_b32 s11, s8, 3
	s_lshr_b32 s12, s8, 2
	s_lshl_b32 s12, s12, 6
	v_add_u32_e32 v236, s12, v234
	s_lshl_b32 s12, s11, 5
	v_lshl_add_u32 v237, v235, 2, s12
	v_lshl_add_u32 v230, v236, 4, v235
	s_lshl_b32 s12, s11, 2
	v_add_u32_e32 v230, s12, v230
	v_lshlrev_b32_e32 v230, 2, v230
	s_lshl_b32 s12, s10, 8
	v_add_u32_e32 v229, s12, v237
	v_lshlrev_b32_e32 v229, 2, v229
	s_lshl_b32 s12, s9, 8
	v_add_u32_e32 v228, s12, v236
	v_lshl_add_u32 v228, v228, 12, v229
	s_sub_u32 s11, s9, 32
	s_lshr_b32 s11, s11, 4
	s_add_u32 s11, s11, 1
	s_cmp_lt_u32 s9, 32
	s_cselect_b32 s11, 0, s11
	s_mul_i32 s11, s11, 0x6000
	s_add_u32 s11, s11, 0x5000
	s_add_u32 s46, s40, s11
	s_addc_u32 s47, s41, 0
	s_add_u32 s50, s40, 0xf984000
	s_addc_u32 s51, s41, 0
	global_load_dwordx4 v[144:147], v229, s[46:47]
	global_load_dwordx4 v[148:151], v229, s[46:47] offset:64
	global_load_dwordx4 v[152:155], v229, s[46:47] offset:512
	global_load_dwordx4 v[156:159], v229, s[46:47] offset:576
	global_load_dwordx4 v[212:215], v229, s[44:45]
	global_load_dwordx4 v[216:219], v229, s[44:45] offset:64
	global_load_dwordx4 v[220:223], v229, s[44:45] offset:512
	global_load_dwordx4 v[224:227], v229, s[44:45] offset:576
	s_add_u32 s48, s42, 0x0
	s_addc_u32 s49, s43, 0
	global_load_dwordx4 v[180:183], v228, s[48:49] nt
	global_load_dwordx4 v[184:187], v228, s[48:49] offset:64 nt
	global_load_dwordx4 v[188:191], v228, s[48:49] offset:512 nt
	global_load_dwordx4 v[192:195], v228, s[48:49] offset:576 nt
	s_add_u32 s48, s42, 0x10000
	s_addc_u32 s49, s43, 0
	global_load_dwordx4 v[196:199], v228, s[48:49] nt
	global_load_dwordx4 v[200:203], v228, s[48:49] offset:64 nt
	global_load_dwordx4 v[204:207], v228, s[48:49] offset:512 nt
	global_load_dwordx4 v[208:211], v228, s[48:49] offset:576 nt
	s_waitcnt vmcnt(4)
	v_pk_fma_f32 v[140:141], v[140:141], v[144:145], v[180:181]
	v_pk_fma_f32 v[142:143], v[142:143], v[146:147], v[182:183]
	v_pk_fma_f32 v[136:137], v[136:137], v[148:149], v[184:185]
	v_pk_fma_f32 v[138:139], v[138:139], v[150:151], v[186:187]
	v_pk_fma_f32 v[132:133], v[132:133], v[152:153], v[188:189]
	v_pk_fma_f32 v[134:135], v[134:135], v[154:155], v[190:191]
	v_pk_fma_f32 v[128:129], v[128:129], v[156:157], v[192:193]
	v_pk_fma_f32 v[130:131], v[130:131], v[158:159], v[194:195]
	v_mul_f32_e32 v232, v140, v140
	v_fmac_f32_e32 v232, v141, v141
	v_fmac_f32_e32 v232, v142, v142
	v_fmac_f32_e32 v232, v143, v143
	v_fmac_f32_e32 v232, v136, v136
	v_fmac_f32_e32 v232, v137, v137
	v_fmac_f32_e32 v232, v138, v138
	v_fmac_f32_e32 v232, v139, v139
	v_fmac_f32_e32 v232, v132, v132
	v_fmac_f32_e32 v232, v133, v133
	v_fmac_f32_e32 v232, v134, v134
	v_fmac_f32_e32 v232, v135, v135
	v_fmac_f32_e32 v232, v128, v128
	v_fmac_f32_e32 v232, v129, v129
	v_fmac_f32_e32 v232, v130, v130
	v_fmac_f32_e32 v232, v131, v131
	ds_write_b32 v230, v232 offset:0
	s_add_u32 s48, s42, 0x20000
	s_addc_u32 s49, s43, 0
	global_load_dwordx4 v[180:183], v228, s[48:49] nt
	global_load_dwordx4 v[184:187], v228, s[48:49] offset:64 nt
	global_load_dwordx4 v[188:191], v228, s[48:49] offset:512 nt
	global_load_dwordx4 v[192:195], v228, s[48:49] offset:576 nt
	s_waitcnt vmcnt(4)
	v_pk_fma_f32 v[124:125], v[124:125], v[144:145], v[196:197]
	v_pk_fma_f32 v[126:127], v[126:127], v[146:147], v[198:199]
	v_pk_fma_f32 v[120:121], v[120:121], v[148:149], v[200:201]
	v_pk_fma_f32 v[122:123], v[122:123], v[150:151], v[202:203]
	v_pk_fma_f32 v[116:117], v[116:117], v[152:153], v[204:205]
	v_pk_fma_f32 v[118:119], v[118:119], v[154:155], v[206:207]
	v_pk_fma_f32 v[112:113], v[112:113], v[156:157], v[208:209]
	v_pk_fma_f32 v[114:115], v[114:115], v[158:159], v[210:211]
	v_mul_f32_e32 v232, v124, v124
	v_fmac_f32_e32 v232, v125, v125
	v_fmac_f32_e32 v232, v126, v126
	v_fmac_f32_e32 v232, v127, v127
	v_fmac_f32_e32 v232, v120, v120
	v_fmac_f32_e32 v232, v121, v121
	v_fmac_f32_e32 v232, v122, v122
	v_fmac_f32_e32 v232, v123, v123
	v_fmac_f32_e32 v232, v116, v116
	v_fmac_f32_e32 v232, v117, v117
	v_fmac_f32_e32 v232, v118, v118
	v_fmac_f32_e32 v232, v119, v119
	v_fmac_f32_e32 v232, v112, v112
	v_fmac_f32_e32 v232, v113, v113
	v_fmac_f32_e32 v232, v114, v114
	v_fmac_f32_e32 v232, v115, v115
	ds_write_b32 v230, v232 offset:1024
	s_add_u32 s48, s42, 0x30000
	s_addc_u32 s49, s43, 0
	global_load_dwordx4 v[196:199], v228, s[48:49] nt
	global_load_dwordx4 v[200:203], v228, s[48:49] offset:64 nt
	global_load_dwordx4 v[204:207], v228, s[48:49] offset:512 nt
	global_load_dwordx4 v[208:211], v228, s[48:49] offset:576 nt
	s_waitcnt vmcnt(4)
	v_pk_fma_f32 v[108:109], v[108:109], v[144:145], v[180:181]
	v_pk_fma_f32 v[110:111], v[110:111], v[146:147], v[182:183]
	v_pk_fma_f32 v[104:105], v[104:105], v[148:149], v[184:185]
	v_pk_fma_f32 v[106:107], v[106:107], v[150:151], v[186:187]
	v_pk_fma_f32 v[96:97], v[96:97], v[152:153], v[188:189]
	v_pk_fma_f32 v[98:99], v[98:99], v[154:155], v[190:191]
	v_pk_fma_f32 v[88:89], v[88:89], v[156:157], v[192:193]
	v_pk_fma_f32 v[90:91], v[90:91], v[158:159], v[194:195]
	v_mul_f32_e32 v232, v108, v108
	v_fmac_f32_e32 v232, v109, v109
	v_fmac_f32_e32 v232, v110, v110
	v_fmac_f32_e32 v232, v111, v111
	v_fmac_f32_e32 v232, v104, v104
	v_fmac_f32_e32 v232, v105, v105
	v_fmac_f32_e32 v232, v106, v106
	v_fmac_f32_e32 v232, v107, v107
	v_fmac_f32_e32 v232, v96, v96
	v_fmac_f32_e32 v232, v97, v97
	v_fmac_f32_e32 v232, v98, v98
	v_fmac_f32_e32 v232, v99, v99
	v_fmac_f32_e32 v232, v88, v88
	v_fmac_f32_e32 v232, v89, v89
	v_fmac_f32_e32 v232, v90, v90
	v_fmac_f32_e32 v232, v91, v91
	ds_write_b32 v230, v232 offset:2048
	s_add_u32 s48, s42, 0x80000
	s_addc_u32 s49, s43, 0
	global_load_dwordx4 v[180:183], v228, s[48:49] nt
	global_load_dwordx4 v[184:187], v228, s[48:49] offset:64 nt
	global_load_dwordx4 v[188:191], v228, s[48:49] offset:512 nt
	global_load_dwordx4 v[192:195], v228, s[48:49] offset:576 nt
	s_waitcnt vmcnt(4)
	v_pk_fma_f32 v[76:77], v[76:77], v[144:145], v[196:197]
	v_pk_fma_f32 v[78:79], v[78:79], v[146:147], v[198:199]
	v_pk_fma_f32 v[72:73], v[72:73], v[148:149], v[200:201]
	v_pk_fma_f32 v[74:75], v[74:75], v[150:151], v[202:203]
	v_pk_fma_f32 v[68:69], v[68:69], v[152:153], v[204:205]
	v_pk_fma_f32 v[70:71], v[70:71], v[154:155], v[206:207]
	v_pk_fma_f32 v[64:65], v[64:65], v[156:157], v[208:209]
	v_pk_fma_f32 v[66:67], v[66:67], v[158:159], v[210:211]
	v_mul_f32_e32 v232, v76, v76
	v_fmac_f32_e32 v232, v77, v77
	v_fmac_f32_e32 v232, v78, v78
	v_fmac_f32_e32 v232, v79, v79
	v_fmac_f32_e32 v232, v72, v72
	v_fmac_f32_e32 v232, v73, v73
	v_fmac_f32_e32 v232, v74, v74
	v_fmac_f32_e32 v232, v75, v75
	v_fmac_f32_e32 v232, v68, v68
	v_fmac_f32_e32 v232, v69, v69
	v_fmac_f32_e32 v232, v70, v70
	v_fmac_f32_e32 v232, v71, v71
	v_fmac_f32_e32 v232, v64, v64
	v_fmac_f32_e32 v232, v65, v65
	v_fmac_f32_e32 v232, v66, v66
	v_fmac_f32_e32 v232, v67, v67
	ds_write_b32 v230, v232 offset:3072
	s_add_u32 s48, s42, 0x90000
	s_addc_u32 s49, s43, 0
	global_load_dwordx4 v[196:199], v228, s[48:49] nt
	global_load_dwordx4 v[200:203], v228, s[48:49] offset:64 nt
	global_load_dwordx4 v[204:207], v228, s[48:49] offset:512 nt
	global_load_dwordx4 v[208:211], v228, s[48:49] offset:576 nt
	s_waitcnt vmcnt(4)
	v_pk_fma_f32 v[60:61], v[60:61], v[144:145], v[180:181]
	v_pk_fma_f32 v[62:63], v[62:63], v[146:147], v[182:183]
	v_pk_fma_f32 v[56:57], v[56:57], v[148:149], v[184:185]
	v_pk_fma_f32 v[58:59], v[58:59], v[150:151], v[186:187]
	v_pk_fma_f32 v[52:53], v[52:53], v[152:153], v[188:189]
	v_pk_fma_f32 v[54:55], v[54:55], v[154:155], v[190:191]
	v_pk_fma_f32 v[48:49], v[48:49], v[156:157], v[192:193]
	v_pk_fma_f32 v[50:51], v[50:51], v[158:159], v[194:195]
	v_mul_f32_e32 v232, v60, v60
	v_fmac_f32_e32 v232, v61, v61
	v_fmac_f32_e32 v232, v62, v62
	v_fmac_f32_e32 v232, v63, v63
	v_fmac_f32_e32 v232, v56, v56
	v_fmac_f32_e32 v232, v57, v57
	v_fmac_f32_e32 v232, v58, v58
	v_fmac_f32_e32 v232, v59, v59
	v_fmac_f32_e32 v232, v52, v52
	v_fmac_f32_e32 v232, v53, v53
	v_fmac_f32_e32 v232, v54, v54
	v_fmac_f32_e32 v232, v55, v55
	v_fmac_f32_e32 v232, v48, v48
	v_fmac_f32_e32 v232, v49, v49
	v_fmac_f32_e32 v232, v50, v50
	v_fmac_f32_e32 v232, v51, v51
	ds_write_b32 v230, v232 offset:8192
	s_add_u32 s48, s42, 0xa0000
	s_addc_u32 s49, s43, 0
	global_load_dwordx4 v[180:183], v228, s[48:49] nt
	global_load_dwordx4 v[184:187], v228, s[48:49] offset:64 nt
	global_load_dwordx4 v[188:191], v228, s[48:49] offset:512 nt
	global_load_dwordx4 v[192:195], v228, s[48:49] offset:576 nt
	s_waitcnt vmcnt(4)
	v_pk_fma_f32 v[44:45], v[44:45], v[144:145], v[196:197]
	v_pk_fma_f32 v[46:47], v[46:47], v[146:147], v[198:199]
	v_pk_fma_f32 v[40:41], v[40:41], v[148:149], v[200:201]
	v_pk_fma_f32 v[42:43], v[42:43], v[150:151], v[202:203]
	v_pk_fma_f32 v[36:37], v[36:37], v[152:153], v[204:205]
	v_pk_fma_f32 v[38:39], v[38:39], v[154:155], v[206:207]
	v_pk_fma_f32 v[32:33], v[32:33], v[156:157], v[208:209]
	v_pk_fma_f32 v[34:35], v[34:35], v[158:159], v[210:211]
	v_mul_f32_e32 v232, v44, v44
	v_fmac_f32_e32 v232, v45, v45
	v_fmac_f32_e32 v232, v46, v46
	v_fmac_f32_e32 v232, v47, v47
	v_fmac_f32_e32 v232, v40, v40
	v_fmac_f32_e32 v232, v41, v41
	v_fmac_f32_e32 v232, v42, v42
	v_fmac_f32_e32 v232, v43, v43
	v_fmac_f32_e32 v232, v36, v36
	v_fmac_f32_e32 v232, v37, v37
	v_fmac_f32_e32 v232, v38, v38
	v_fmac_f32_e32 v232, v39, v39
	v_fmac_f32_e32 v232, v32, v32
	v_fmac_f32_e32 v232, v33, v33
	v_fmac_f32_e32 v232, v34, v34
	v_fmac_f32_e32 v232, v35, v35
	ds_write_b32 v230, v232 offset:9216
	s_add_u32 s48, s42, 0xb0000
	s_addc_u32 s49, s43, 0
	global_load_dwordx4 v[196:199], v228, s[48:49] nt
	global_load_dwordx4 v[200:203], v228, s[48:49] offset:64 nt
	global_load_dwordx4 v[204:207], v228, s[48:49] offset:512 nt
	global_load_dwordx4 v[208:211], v228, s[48:49] offset:576 nt
	s_waitcnt vmcnt(4)
	v_pk_fma_f32 v[28:29], v[28:29], v[144:145], v[180:181]
	v_pk_fma_f32 v[30:31], v[30:31], v[146:147], v[182:183]
	v_pk_fma_f32 v[24:25], v[24:25], v[148:149], v[184:185]
	v_pk_fma_f32 v[26:27], v[26:27], v[150:151], v[186:187]
	v_pk_fma_f32 v[16:17], v[16:17], v[152:153], v[188:189]
	v_pk_fma_f32 v[18:19], v[18:19], v[154:155], v[190:191]
	v_pk_fma_f32 v[8:9], v[8:9], v[156:157], v[192:193]
	v_pk_fma_f32 v[10:11], v[10:11], v[158:159], v[194:195]
	v_mul_f32_e32 v232, v28, v28
	v_fmac_f32_e32 v232, v29, v29
	v_fmac_f32_e32 v232, v30, v30
	v_fmac_f32_e32 v232, v31, v31
	v_fmac_f32_e32 v232, v24, v24
	v_fmac_f32_e32 v232, v25, v25
	v_fmac_f32_e32 v232, v26, v26
	v_fmac_f32_e32 v232, v27, v27
	v_fmac_f32_e32 v232, v16, v16
	v_fmac_f32_e32 v232, v17, v17
	v_fmac_f32_e32 v232, v18, v18
	v_fmac_f32_e32 v232, v19, v19
	v_fmac_f32_e32 v232, v8, v8
	v_fmac_f32_e32 v232, v9, v9
	v_fmac_f32_e32 v232, v10, v10
	v_fmac_f32_e32 v232, v11, v11
	ds_write_b32 v230, v232 offset:10240
	s_waitcnt vmcnt(0)
	v_pk_fma_f32 v[20:21], v[20:21], v[144:145], v[196:197]
	v_pk_fma_f32 v[22:23], v[22:23], v[146:147], v[198:199]
	v_pk_fma_f32 v[12:13], v[12:13], v[148:149], v[200:201]
	v_pk_fma_f32 v[14:15], v[14:15], v[150:151], v[202:203]
	v_pk_fma_f32 v[4:5], v[4:5], v[152:153], v[204:205]
	v_pk_fma_f32 v[6:7], v[6:7], v[154:155], v[206:207]
	v_pk_fma_f32 v[0:1], v[0:1], v[156:157], v[208:209]
	v_pk_fma_f32 v[2:3], v[2:3], v[158:159], v[210:211]
	v_mul_f32_e32 v232, v20, v20
	v_fmac_f32_e32 v232, v21, v21
	v_fmac_f32_e32 v232, v22, v22
	v_fmac_f32_e32 v232, v23, v23
	v_fmac_f32_e32 v232, v12, v12
	v_fmac_f32_e32 v232, v13, v13
	v_fmac_f32_e32 v232, v14, v14
	v_fmac_f32_e32 v232, v15, v15
	v_fmac_f32_e32 v232, v4, v4
	v_fmac_f32_e32 v232, v5, v5
	v_fmac_f32_e32 v232, v6, v6
	v_fmac_f32_e32 v232, v7, v7
	v_fmac_f32_e32 v232, v0, v0
	v_fmac_f32_e32 v232, v1, v1
	v_fmac_f32_e32 v232, v2, v2
	v_fmac_f32_e32 v232, v3, v3
	ds_write_b32 v230, v232 offset:11264
	s_waitcnt lgkmcnt(0)
	s_barrier
	v_cmp_gt_u32_e32 vcc, 0x100, v177
	s_and_saveexec_b64 s[0:1], vcc
	s_cbranch_execz .Lfz_nored
	v_lshlrev_b32_e32 v233, 6, v177
	ds_read_b128 v[236:239], v233
	ds_read_b128 v[240:243], v233 offset:16
	ds_read_b128 v[244:247], v233 offset:32
	ds_read_b128 v[248:251], v233 offset:48
	s_lshl_b32 s11, s9, 8
	v_add_u32_e32 v234, s11, v177
	v_lshlrev_b32_e32 v234, 4, v234
	s_lshl_b32 s11, s10, 2
	v_add_u32_e32 v234, s11, v234
	s_waitcnt lgkmcnt(0)
	v_add_f32_e32 v236, v236, v237
	v_add_f32_e32 v236, v236, v238
	v_add_f32_e32 v236, v236, v239
	v_add_f32_e32 v236, v236, v240
	v_add_f32_e32 v236, v236, v241
	v_add_f32_e32 v236, v236, v242
	v_add_f32_e32 v236, v236, v243
	v_add_f32_e32 v236, v236, v244
	v_add_f32_e32 v236, v236, v245
	v_add_f32_e32 v236, v236, v246
	v_add_f32_e32 v236, v236, v247
	v_add_f32_e32 v236, v236, v248
	v_add_f32_e32 v236, v236, v249
	v_add_f32_e32 v236, v236, v250
	v_add_f32_e32 v236, v236, v251
	global_store_dword v234, v236, s[50:51]
